# merge->out barrier XCD-local (with xcc-id mapping check + global fallback); layer-1 w_in re-conversion moved behind the global out->norm barrier
# speedup vs baseline: 1.0084x; 1.0084x over previous
.LBB0_14:
	s_load_dwordx16 s[4:19], s[0:1], 0x0
	s_add_u32 s0, s96, 0x10ad8100
	s_addc_u32 s1, s97, 0
	s_waitcnt lgkmcnt(0)
	s_barrier
	v_writelane_b32 v253, s4, 8
	s_nop 1
	v_writelane_b32 v253, s5, 9
	v_writelane_b32 v253, s6, 10
	v_writelane_b32 v253, s7, 11
	v_writelane_b32 v253, s8, 12
	v_writelane_b32 v253, s9, 13
	v_writelane_b32 v253, s10, 14
	v_writelane_b32 v253, s11, 15
	v_writelane_b32 v253, s12, 16
	v_writelane_b32 v253, s13, 17
	v_writelane_b32 v253, s14, 18
	v_writelane_b32 v253, s15, 19
	v_writelane_b32 v253, s16, 20
	v_writelane_b32 v253, s17, 21
	v_writelane_b32 v253, s18, 22
	v_writelane_b32 v253, s19, 23
	v_writelane_b32 v253, s0, 24
	s_nop 1
	v_writelane_b32 v253, s1, 25
	s_getreg_b32 s0, hwreg(HW_REG_XCC_ID, 0, 4)
	s_and_b32 s53, s0, 15
	s_and_saveexec_b64 s[0:1], s[54:55]
	s_cbranch_execz .LBB0_17
	s_mov_b64 s[4:5], exec
	v_mbcnt_lo_u32_b32 v0, s4, 0
	v_mbcnt_hi_u32_b32 v0, s5, v0
	v_cmp_eq_u32_e32 vcc, 0, v0
	s_and_b64 s[6:7], exec, vcc
	s_mov_b64 exec, s[6:7]
	s_cbranch_execz .LBB0_17
	s_bcnt1_i32_b64 s4, s[4:5]
	s_lshl_b32 s3, s53, 8
	v_mov_b32_e32 v1, s4
	v_readlane_b32 s4, v253, 24
	v_mov_b32_e32 v0, s3
	v_readlane_b32 s5, v253, 25
	s_nop 4
	global_atomic_add v0, v1, s[4:5] offset:1024
	s_and_b32 s3, s52, 7
	s_xor_b32 s3, s3, 0
	s_cmp_eq_u32 s3, s53
	s_cbranch_scc1 .Lxmap_ok
	v_mov_b32_e32 v2, 0
	global_atomic_add v2, v1, s[4:5]
.Lxmap_ok:
.LBB0_17:
	s_or_b64 exec, exec, s[0:1]
	s_mov_b64 s[0:1], 0
	s_add_u32 s6, s96, s0
	s_addc_u32 s7, s97, s1
	v_mov_b32_e32 v48, v197
	v_mov_b32_e32 v10, v197
	s_cmpk_gt_i32 s52, 0xc7f
	s_cbranch_scc1 .LBB0_78
	s_cmpk_lt_i32 s52, 0x880
	s_cselect_b64 s[0:1], -1, 0
	s_cmpk_gt_i32 s52, 0x87f
	s_cbranch_scc0 .LBB0_20
	s_add_i32 s3, s52, 0xfffff780
	v_readlane_b32 s8, v253, 0
	s_cmpk_lt_u32 s3, 0x200
	s_mov_b32 s4, 0x10100000
	v_readlane_b32 s9, v253, 1
	v_readlane_b32 s12, v253, 4
	v_readlane_b32 s13, v253, 5
	v_readlane_b32 s14, v253, 6
	v_readlane_b32 s15, v253, 7
	s_cselect_b32 s4, s4, 0x10500000
	s_cselect_b32 s5, s13, s15
	s_cselect_b32 s8, s12, s14
	s_lshl_b32 s9, s3, 12
	v_readlane_b32 s10, v253, 2
	s_and_b32 s9, s9, 0x100000
	s_lshl_b32 s10, s9, 2
	s_add_u32 s12, s8, s10
	s_addc_u32 s13, s5, 0
	s_add_u32 s4, s6, s4
	s_addc_u32 s5, s7, 0
	s_lshl_b32 s8, s9, 1
	s_add_u32 s4, s4, s8
	v_readlane_b32 s11, v253, 3
	s_addc_u32 s5, s5, 0
	s_lshl_b32 s3, s3, 2
	s_and_b32 s8, s3, 0x3c0
	s_lshl_b32 s3, s52, 2
	s_mov_b64 s[14:15], 0x400
	s_mov_b32 s11, s8
	s_cbranch_execz .LBB0_21
	s_branch .LBB0_37

.LBB0_175:
	s_or_b64 exec, exec, s[0:1]
	v_readlane_b32 s4, v253, 24
	v_readlane_b32 s5, v253, 25
	v_mov_b32_e32 v254, 0
	s_nop 4
	global_load_dword v254, v254, s[4:5] sc1
	s_waitcnt vmcnt(0)
	s_mul_i32 s0, s99, s98
	s_mul_i32 s60, s0, s2
	s_mul_i32 s0, s98, 5
	s_lshl_b32 s58, s52, 3
	s_lshl_b32 s57, s98, 3
	s_lshl_b32 s59, s98, 4
	s_add_i32 s0, s0, s52
	s_cmpk_gt_i32 s0, 0x57f
	s_cselect_b64 s[0:1], -1, 0
	v_writelane_b32 v253, s0, 26
	s_cmpk_lt_u32 s52, 0x580
	s_waitcnt lgkmcnt(0)
	v_and_b32_e32 v0, 63, v197
	v_writelane_b32 v253, s1, 27
	s_cselect_b64 s[0:1], -1, 0
	v_writelane_b32 v253, s0, 28
	v_mbcnt_lo_u32_b32 v1, -1, 0
	v_mbcnt_hi_u32_b32 v218, -1, v1
	v_writelane_b32 v253, s1, 29
	s_and_b32 s0, s52, 7
	s_lshr_b32 s1, s52, 3
	s_mul_i32 s2, s0, 0xb0
	s_add_i32 s1, s2, s1
	s_mul_i32 s2, s1, 0xba2f
	s_lshr_b32 s2, s2, 23
	s_lshl_b32 s3, s2, 3
	s_mulk_i32 s2, 0xb0
	s_sub_i32 s2, s1, s2
	s_and_b32 s4, s2, 7
	s_or_b32 s3, s4, s3
	v_writelane_b32 v253, s3, 30
	s_lshl_b32 s3, s3, 19
	s_bfe_u32 s2, s2, 0xd0003
	v_writelane_b32 v253, s3, 31
	v_writelane_b32 v253, s2, 32
	s_lshl_b32 s2, s2, 19
	s_cmpk_lt_i32 s52, 0x200
	v_writelane_b32 v253, s2, 33
	s_cselect_b64 s[2:3], -1, 0
	v_writelane_b32 v253, s2, 34
	s_cmpk_lt_i32 s52, 0x300
	s_mulk_i32 s0, 0xffb0
	v_writelane_b32 v253, s3, 35
	s_cselect_b64 s[2:3], -1, 0
	v_writelane_b32 v253, s2, 36
	s_cmpk_lt_i32 s52, 0x100
	v_and_b32_e32 v1, 64, v218
	v_writelane_b32 v253, s3, 37
	s_cselect_b64 s[2:3], -1, 0
	s_lshl_b32 s61, s98, 9
	v_writelane_b32 v253, s2, 38
	s_cmpk_lt_u32 s52, 0x300
	s_mov_b32 s91, 0
	v_writelane_b32 v253, s3, 39
	s_cselect_b64 s[2:3], -1, 0
	s_add_i32 s0, s1, s0
	s_mul_i32 s1, s0, 0xaaab
	v_writelane_b32 v253, s2, 40
	s_lshr_b32 s1, s1, 22
	s_movk_i32 s62, 0x60
	v_writelane_b32 v253, s3, 41
	s_lshl_b32 s2, s1, 3
	s_mulk_i32 s1, 0x60
	s_sub_i32 s0, s0, s1
	s_and_b32 s1, s0, 7
	s_or_b32 s1, s1, s2
	v_writelane_b32 v253, s1, 42
	s_lshl_b32 s1, s1, 19
	s_bfe_u32 s0, s0, 0xd0003
	v_writelane_b32 v253, s1, 43
	v_writelane_b32 v253, s0, 44
	s_lshl_b32 s0, s0, 19
	s_cmpk_lt_u32 s52, 0x100
	v_writelane_b32 v253, s0, 45
	s_cselect_b64 s[0:1], -1, 0
	v_writelane_b32 v253, s0, 46
	s_lshr_b32 s64, s52, 6
	s_lshl_b32 s66, s64, 19
	v_writelane_b32 v253, s1, 47
	s_and_b32 s0, s58, 56
	s_bfe_u32 s1, s52, 0x30003
	s_or_b32 s63, s1, s0
	s_lshl_b32 s65, s63, 19
	s_cmpk_lt_i32 s52, 0x880
	s_cselect_b64 s[0:1], -1, 0
	v_writelane_b32 v253, s0, 48
	s_movk_i32 s99, 0x600
	s_movk_i32 s71, 0x4000
	v_writelane_b32 v253, s1, 49
	v_mov_b32_e32 v195, 0
	v_readlane_b32 s0, v253, 8
	v_readlane_b32 s4, v253, 12
	v_readlane_b32 s12, v253, 20
	v_readlane_b32 s5, v253, 13
	v_readlane_b32 s6, v253, 14
	v_readlane_b32 s13, v253, 21
	s_add_u32 s4, s12, 0x2200000
	v_readlane_b32 s7, v253, 15
	s_addc_u32 s5, s13, 0
	s_lshl_b32 s6, s52, 2
	s_and_b32 s7, s6, 0xffffffc0
	v_readlane_b32 s1, v253, 9
	s_cmpk_lt_i32 s7, 0x400
	v_readlane_b32 s2, v253, 10
	v_readlane_b32 s3, v253, 11
	s_cselect_b64 s[0:1], -1, 0
	s_cmpk_lt_u32 s6, 0x600
	s_cselect_b64 s[2:3], -1, 0
	s_or_b64 s[0:1], s[0:1], s[2:3]
	s_add_i32 s2, s7, 0xfffff700
	s_cmpk_lt_u32 s6, 0x1200
	v_readlane_b32 s8, v253, 16
	v_readlane_b32 s9, v253, 17
	v_readlane_b32 s10, v253, 18
	v_readlane_b32 s11, v253, 19
	v_readlane_b32 s14, v253, 22
	v_readlane_b32 s15, v253, 23
	v_writelane_b32 v253, s7, 50
	s_cselect_b32 s2, s2, s6
	s_lshl_b32 s7, s52, 6
	v_writelane_b32 v253, s7, 51
	s_and_b32 s7, s7, 0x3c0
	s_add_i32 s3, s6, 0x300
	v_writelane_b32 v253, s7, 52
	s_or_b32 s7, s7, 32
	s_cmpk_lt_u32 s6, 0xf00
	s_cselect_b32 s2, s3, s2
	s_and_b64 s[0:1], s[0:1], exec
	s_cselect_b32 s0, s6, s2
	v_writelane_b32 v253, s7, 53
	s_and_b32 s2, s0, 0xffffffc0
	v_writelane_b32 v253, s6, 54
	s_mov_b32 s0, s2
	s_ashr_i32 s3, s2, 31
	v_writelane_b32 v253, s0, 55
	s_mov_b32 s72, 0x800000
	v_mov_b32_e32 v220, 0x3000
	v_writelane_b32 v253, s1, 56
	s_lshl_b64 s[0:1], s[2:3], 2
	s_add_u32 s0, s4, s0
	v_writelane_b32 v253, s4, 57
	s_addc_u32 s1, s5, s1
	s_lshl_b32 s67, s98, 1
	v_writelane_b32 v253, s5, 58
	v_writelane_b32 v253, s0, 59
	s_lshl_b32 s69, s98, 10
	s_lshl_b32 s70, s98, 14
	v_writelane_b32 v253, s1, 60
	s_lshl_b32 s0, s52, 1
	v_writelane_b32 v253, s0, 61
	s_lshl_b32 s0, s52, 12
	v_writelane_b32 v253, s0, 62
	s_add_i32 s0, s52, s98
	s_lshl_b32 s1, s0, 2
	s_lshl_b32 s0, s0, 6
	v_writelane_b32 v253, s1, 63
	v_writelane_b32 v252, s0, 0
	v_cmp_eq_u32_e64 s[0:1], 0, v0
	s_add_i32 s73, 0, 0x20f80
	s_add_i32 s74, 0, 0x20f84
	v_writelane_b32 v252, s0, 1
	s_lshl_b32 s68, s98, 2
	s_lshl_b32 s85, s98, 6
	v_writelane_b32 v252, s1, 2
	v_writelane_b32 v252, s52, 3
	v_writelane_b32 v252, s54, 4
	v_mov_b32_e32 v221, 1
	v_mov_b32_e32 v225, 0xbf4ccccd
	v_writelane_b32 v252, s55, 5
	v_writelane_b32 v252, s53, 6
	v_writelane_b32 v252, s56, 7
	v_writelane_b32 v252, s57, 8
	v_writelane_b32 v252, s58, 9
	v_writelane_b32 v252, s59, 10
	v_writelane_b32 v252, s60, 11
	v_writelane_b32 v252, s61, 12
	v_writelane_b32 v252, s63, 13
	v_writelane_b32 v252, s64, 14
	v_writelane_b32 v252, s65, 15
	v_writelane_b32 v252, s66, 16
	v_writelane_b32 v252, s67, 17
	v_writelane_b32 v252, s69, 18
	v_writelane_b32 v252, s70, 19
	v_writelane_b32 v252, s73, 20
	v_mov_b32_e32 v227, 0x260
	v_mov_b32_e32 v228, 0x3c23d70a
	v_mov_b32_e32 v196, 0x358637bd
	v_add_u32_e32 v219, 64, v1
	v_xor_b32_e32 v230, 32, v218
	v_xor_b32_e32 v229, 16, v218
	v_xor_b32_e32 v226, 8, v218
	v_xor_b32_e32 v224, 4, v218
	v_xor_b32_e32 v223, 2, v218
	v_xor_b32_e32 v222, 1, v218
	v_mov_b64_e32 v[198:199], 0x57f
	v_mov_b32_e32 v231, 0xfcf
	v_mov_b32_e32 v232, 0xff800000
	v_mov_b32_e32 v233, 0x41b17218
	v_mov_b32_e32 v234, 0x20ba0
	v_mov_b64_e32 v[200:201], 0x2ff
	v_mov_b64_e32 v[202:203], 0xff
	v_mov_b32_e32 v235, 0xbfb8aa3b
	s_movk_i32 s75, 0xfff
	s_movk_i32 s78, 0xfdf
	s_movk_i32 s84, 0xfef
	s_movk_i32 s41, 0x70
	s_movk_i32 s33, 0xff7e
	s_mov_b32 s86, 0x42800000
	s_mov_b32 s79, 0x9000000
	s_mov_b32 s80, 0x80000
	s_movk_i32 s81, 0x1800
	s_mov_b64 s[2:3], -1
	s_mov_b64 s[82:83], 0x80
	s_mov_b32 s76, s91
	v_writelane_b32 v252, s74, 21
	s_barrier
	v_writelane_b32 v252, s85, 22
	s_branch .LBB0_178

.LBB0_177:
	s_or_b64 exec, exec, s[0:1]
	s_mov_b32 s32, 3
	s_mov_b32 s2, s96
	s_mov_b32 s3, s97
	s_branch .LBB0_771
.Lcvt_ret:
	s_mov_b32 s32, 0
	v_readlane_b32 s0, v252, 27
	v_readlane_b32 s1, v252, 28
	s_mov_b32 s76, 1
	s_mov_b64 s[2:3], 0
	s_and_b64 vcc, exec, s[0:1]
	s_waitcnt lgkmcnt(0)
	s_barrier
	s_cbranch_vccnz .LBB0_859

.LBB0_739:
	s_andn2_saveexec_b64 s[8:9], s[8:9]
	s_cbranch_execz .LBB0_759
	s_mov_b64 s[8:9], exec
	v_readfirstlane_b32 s3, v254
	s_nop 3
	s_cmp_eq_u32 s3, 0
	s_cbranch_scc1 .LBB0_756
	buffer_wbl2 sc1
	s_waitcnt lgkmcnt(0)
	s_waitcnt vmcnt(0)
	v_mbcnt_lo_u32_b32 v1, s8, 0
	v_mbcnt_hi_u32_b32 v1, s9, v1
	v_cmp_eq_u32_e32 vcc, 0, v1
	s_and_saveexec_b64 s[10:11], vcc
	s_cbranch_execz .LBB0_742
	s_bcnt1_i32_b64 s3, s[8:9]
	v_mov_b32_e32 v2, s3
	global_atomic_add v2, v220, v2, s[6:7] offset:1024 sc0

.LBB0_771:
	v_readlane_b32 s0, v252, 23
	v_readlane_b32 s1, v252, 24
	s_andn2_b64 vcc, exec, s[0:1]
	s_waitcnt lgkmcnt(0)
	s_barrier
	s_cmp_lg_u32 s32, 3
	s_cbranch_scc1 .LBB0_808
	s_cbranch_vccnz .LBB0_808
	v_readlane_b32 s0, v253, 48
	v_readlane_b32 s1, v253, 49
	v_mov_b32_e32 v8, v197
	s_andn2_b64 vcc, exec, s[0:1]
	s_cbranch_vccnz .LBB0_808
	v_readlane_b32 s0, v253, 59
	v_ashrrev_i32_e32 v12, 4, v8
	v_lshlrev_b32_e32 v0, 2, v8
	v_readlane_b32 s4, v253, 52
	v_readlane_b32 s1, v253, 60
	v_and_b32_e32 v10, 60, v0
	v_add_u32_e32 v2, s4, v12
	v_mov_b64_e32 v[0:1], s[0:1]
	s_mov_b32 s5, 0x8800
	v_mad_i64_i32 v[2:3], s[0:1], v2, s5, v[0:1]
	v_readlane_b32 s0, v253, 53
	v_lshlrev_b32_e32 v194, 2, v10
	v_lshl_add_u64 v[2:3], v[2:3], 0, v[194:195]
	v_add_u32_e32 v4, s0, v12
	v_mad_i64_i32 v[0:1], s[0:1], v4, s5, v[0:1]
	v_lshl_add_u64 v[4:5], v[0:1], 0, v[194:195]
	global_load_dwordx4 v[0:3], v[2:3], off
	s_nop 0
	global_load_dwordx4 v[4:7], v[4:5], off
	s_add_u32 s0, s2, 0xf000000
	s_movk_i32 s2, 0x104
	v_ashrrev_i32_e32 v14, 3, v8
	v_lshlrev_b32_e32 v8, 3, v8
	v_mul_lo_u32 v9, v12, s2
	v_and_b32_e32 v16, 56, v8
	v_readlane_b32 s6, v253, 55
	s_addc_u32 s1, s3, 0
	v_add3_u32 v13, 0, v9, v194
	v_mad_u32_u24 v15, v16, s2, 0
	v_lshlrev_b32_e32 v8, 2, v10
	v_lshlrev_b32_e32 v194, 1, v16
	v_readlane_b32 s2, v252, 0
	v_readlane_b32 s3, v253, 63
	v_readlane_b32 s10, v253, 50
	s_mov_b32 s5, s6
	s_mov_b32 s23, s52
	v_readlane_b32 s7, v253, 56
	s_branch .LBB0_775

.LBB0_808:
	s_cmp_eq_u32 s32, 3
	s_cbranch_scc1 .Lcvt_ret
	s_waitcnt vmcnt(0)
	s_barrier
	s_and_saveexec_b64 s[0:1], s[54:55]
	s_cbranch_execz .LBB0_177
	s_mov_b32 s2, s53
	s_mov_b64 s[4:5], 0
	s_waitcnt vmcnt(2)
	v_mov_b32_e32 v0, s73
	s_waitcnt vmcnt(0) expcnt(0) lgkmcnt(0)
	ds_read_b32 v2, v0
	v_mov_b32_e32 v0, s74
	ds_read_b32 v0, v0
	s_lshl_b64 s[4:5], s[4:5], 2
	v_readlane_b32 s6, v253, 24
	v_readlane_b32 s7, v253, 25
	s_add_u32 s4, s6, s4
	s_waitcnt lgkmcnt(1)
	v_cmp_ne_u32_e32 vcc, 0, v2
	s_addc_u32 s5, s7, s5
	s_cbranch_vccnz .LBB0_824
	s_add_u32 s6, s4, 0x1000
	s_addc_u32 s7, s5, 0
	s_add_u32 s8, s4, 0x1100
	s_addc_u32 s9, s5, 0
	s_add_u32 s10, s4, 0x1200
	s_addc_u32 s11, s5, 0
	s_add_u32 s12, s4, 0x1300
	s_addc_u32 s13, s5, 0
	s_mov_b32 s3, 1
	s_branch .LBB0_812

	.amdhsa_kernel _Z10mk_forward6Params
		.amdhsa_group_segment_fixed_size 0
		.amdhsa_private_segment_fixed_size 0
		.amdhsa_kernarg_size 376
		.amdhsa_user_sgpr_count 2
		.amdhsa_user_sgpr_dispatch_ptr 0
		.amdhsa_user_sgpr_queue_ptr 0
		.amdhsa_user_sgpr_kernarg_segment_ptr 1
		.amdhsa_user_sgpr_dispatch_id 0
		.amdhsa_user_sgpr_kernarg_preload_length 0
		.amdhsa_user_sgpr_kernarg_preload_offset 0
		.amdhsa_user_sgpr_private_segment_size 0
		.amdhsa_uses_dynamic_stack 0
		.amdhsa_enable_private_segment 0
		.amdhsa_system_sgpr_workgroup_id_x 1
		.amdhsa_system_sgpr_workgroup_id_y 0
		.amdhsa_system_sgpr_workgroup_id_z 0
		.amdhsa_system_sgpr_workgroup_info 0
		.amdhsa_system_vgpr_workitem_id 2
		.amdhsa_next_free_vgpr 256
		.amdhsa_next_free_sgpr 100
		.amdhsa_accum_offset 256
		.amdhsa_reserve_vcc 1
		.amdhsa_float_round_mode_32 0
		.amdhsa_float_round_mode_16_64 0
		.amdhsa_float_denorm_mode_32 3
		.amdhsa_float_denorm_mode_16_64 3
		.amdhsa_dx10_clamp 1
		.amdhsa_ieee_mode 1
		.amdhsa_fp16_overflow 0
		.amdhsa_tg_split 0
		.amdhsa_exception_fp_ieee_invalid_op 0
		.amdhsa_exception_fp_denorm_src 0
		.amdhsa_exception_fp_ieee_div_zero 0
		.amdhsa_exception_fp_ieee_overflow 0
		.amdhsa_exception_fp_ieee_underflow 0
		.amdhsa_exception_fp_ieee_inexact 0
		.amdhsa_exception_int_div_zero 0
	.end_amdhsa_kernel

amdhsa.kernels:
  - .agpr_count:     0
    .args:
      - .offset:         0
        .size:           120
        .value_kind:     by_value
      - .offset:         120
        .size:           4
        .value_kind:     hidden_block_count_x
      - .offset:         124
        .size:           4
        .value_kind:     hidden_block_count_y
      - .offset:         128
        .size:           4
        .value_kind:     hidden_block_count_z
      - .offset:         132
        .size:           2
        .value_kind:     hidden_group_size_x
      - .offset:         134
        .size:           2
        .value_kind:     hidden_group_size_y
      - .offset:         136
        .size:           2
        .value_kind:     hidden_group_size_z
      - .offset:         138
        .size:           2
        .value_kind:     hidden_remainder_x
      - .offset:         140
        .size:           2
        .value_kind:     hidden_remainder_y
      - .offset:         142
        .size:           2
        .value_kind:     hidden_remainder_z
      - .offset:         160
        .size:           8
        .value_kind:     hidden_global_offset_x
      - .offset:         168
        .size:           8
        .value_kind:     hidden_global_offset_y
      - .offset:         176
        .size:           8
        .value_kind:     hidden_global_offset_z
      - .offset:         184
        .size:           2
        .value_kind:     hidden_grid_dims
      - .offset:         208
        .size:           8
        .value_kind:     hidden_multigrid_sync_arg
      - .offset:         240
        .size:           4
        .value_kind:     hidden_dynamic_lds_size
    .group_segment_fixed_size: 0
    .kernarg_segment_align: 8
    .kernarg_segment_size: 376
    .language:       OpenCL C
    .language_version:
      - 2
      - 0
    .max_flat_workgroup_size: 512
    .name:           _Z10mk_forward6Params
    .private_segment_fixed_size: 0
    .sgpr_count:     106
    .sgpr_spill_count: 106
    .symbol:         _Z10mk_forward6Params.kd
    .uniform_work_group_size: 1
    .uses_dynamic_stack: false
    .vgpr_count:     256
    .vgpr_spill_count: 0
    .wavefront_size: 64
